# prologue de-serialisation of the per-unit rstd fill before the W_in and FFN2-up GEMMs: a prefetch pass touches every unit's sum-of-squares line with all loads in flight, so the serial loop's loads hit
# baseline (speedup 1.0000x reference)
;     __host__ __device__ bool next(int i, Unit& u) const {
;         const long L = (long)i * G + c; if (L >= nwg) return false;
;         int wgid = (int)L; { const int q = nwg / NXCD, r = nwg % NXCD, xcd = wgid % NXCD, off = wgid / NXCD; wgid = (xcd < r ? xcd * (q + 1) : r * (q + 1) + (xcd - r) * q) + off; }
;         const int nig = WGM * nN, gid = wgid / nig, fm = gid * WGM, gsz = (nM - fm) < WGM ? (nM - fm) : WGM;
;         u.pm = fm + ((wgid % nig) % gsz); u.pn = (wgid % nig) / gsz; return true;
;     }
; DI void fill_rstd(const pg8::StaticOrder& S, const float* ss, unsigned char* smem) {
;     float* rl = (float*)(smem + 131072);
;     for (int i = 0; i < 16; ++i) { pg8::Unit u; if (!S.next(i, u)) break;
;         if (threadIdx.x < 256) rl[i * 256 + threadIdx.x] = 1.0f / sqrtf(ss[u.pm * 256 + threadIdx.x] * (1.0f / DM) + EPSN); }
;     __syncthreads();
; }
.LBB0_414:
	s_or_b64 exec, exec, s[0:1]
	s_add_u32 s6, s50, 0x9fc0500
	s_waitcnt vmcnt(0)
	v_lshlrev_b32_e32 v10, 2, v206
	s_addc_u32 s7, s51, 0
	s_ashr_i32 s89, s88, 31
	v_add_u32_e32 v1, 0, v10
	s_ashr_i32 s30, s54, 31
	s_mov_b32 s31, s54
	s_mov_b32 s14, 0
	v_add_u32_e32 v1, 0x20000, v1
	s_waitcnt lgkmcnt(0)
	v_mov_b64_e32 v[2:3], 0x3bf
	s_movk_i32 s15, 0x79
	v_mov_b32_e32 v5, 0
	v_mov_b32_e32 v6, 0x358637bd
	s_mov_b32 s16, 0xf800000
	v_mov_b32_e32 v7, 0x260
	s_mov_b64 s[8:9], s[88:89]
	s_and_saveexec_b64 s[12:13], s[4:5]
	s_cbranch_execz .Lrs4_skip
.Lrs4_pf:
	v_cmp_gt_i64_e32 vcc, s[8:9], v[2:3]
	s_cbranch_vccnz .Lrs4_done
	s_ashr_i32 s0, s8, 31
	s_lshr_b32 s0, s0, 29
	s_add_i32 s0, s8, s0
	s_ashr_i32 s1, s0, 3
	s_and_b32 s0, s0, -8
	s_sub_i32 s0, s8, s0
	s_cmp_lt_i32 s0, 0
	s_cselect_b32 s17, s15, 0x78
	s_mul_i32 s0, s0, s17
	s_add_i32 s0, s0, s1
	s_mul_hi_i32 s1, s0, 0x88888889
	s_add_i32 s1, s1, s0
	s_lshr_b32 s17, s1, 31
	s_ashr_i32 s1, s1, 6
	s_add_i32 s1, s1, s17
	s_lshl_b32 s17, s1, 3
	s_sub_i32 s18, 64, s17
	s_min_i32 s18, s18, 8
	s_abs_i32 s18, s18
	v_cvt_f32_u32_e32 v4, s18
	s_sub_i32 s19, 0, s18
	s_mulk_i32 s1, 0x78
	s_sub_i32 s0, s0, s1
	v_rcp_iflag_f32_e32 v4, v4
	s_ashr_i32 s1, s0, 31
	s_abs_i32 s0, s0
	v_mul_f32_e32 v4, 0x4f7ffffe, v4
	v_cvt_u32_f32_e32 v4, v4
	s_nop 0
	v_readfirstlane_b32 s20, v4
	s_mul_i32 s19, s19, s20
	s_mul_hi_u32 s19, s20, s19
	s_add_i32 s20, s20, s19
	s_mul_hi_u32 s19, s0, s20
	s_mul_i32 s19, s19, s18
	s_sub_i32 s0, s0, s19
	s_sub_i32 s19, s0, s18
	s_cmp_ge_u32 s0, s18
	s_cselect_b32 s0, s19, s0
	s_sub_i32 s19, s0, s18
	s_cmp_ge_u32 s0, s18
	s_cselect_b32 s0, s19, s0
	s_xor_b32 s0, s0, s1
	s_sub_i32 s0, s0, s1
	s_add_i32 s0, s0, s17
	v_lshl_or_b32 v4, s0, 8, v206
	v_lshl_add_u64 v[8:9], v[4:5], 2, s[6:7]
	global_load_dword v14, v[8:9], off
	s_addk_i32 s14, 0x400
	s_add_u32 s8, s8, s31
	s_addc_u32 s9, s9, s30
	s_cmpk_lg_i32 s14, 0x4000
	s_cbranch_scc1 .Lrs4_pf
.Lrs4_done:
	s_waitcnt vmcnt(0)
	s_mov_b32 s14, 0
	s_mov_b64 s[8:9], s[88:89]
.Lrs4_skip:
	s_or_b64 exec, exec, s[12:13]
	s_branch .LBB0_417

; #define REP(k) for (int rep_ = 0; rep_ < ((k) == DUP_PH ? 2 : 1); ++rep_, (((k) == DUP_PH && rep_ == 1) ? grid.sync() : (void)0))
; DI void fill_rstd(const pg8::StaticOrder& S, const float* ss, unsigned char* smem) {
;     float* rl = (float*)(smem + 131072);
;     for (int i = 0; i < 16; ++i) { pg8::Unit u; if (!S.next(i, u)) break;
;         if (threadIdx.x < 256) rl[i * 256 + threadIdx.x] = 1.0f / sqrtf(ss[u.pm * 256 + threadIdx.x] * (1.0f / DM) + EPSN); }
;     __syncthreads();
; }
; __global__ void __launch_bounds__(512, 2) hymba_fwd(Params P) {
;     ...
;     if (IN(10)) REP(10) { pg8::Gemm g{(const bf16_t*)(ws + WS_XN), (const bf16_t*)(ws + WS_W13B), MTOK, 2 * DFF, DM};
;         pg8::StaticOrder S; S.init(MTOK, 2 * DFF, G, (int)blockIdx.x); EpiSwiGLU E{(bf16_t*)(ws + WS_H), (const float*)(ws + WS_SMALL) + SM_SS + 16384}; fill_rstd(S, E.ss, shm);
.LBB0_1077:
	s_cmp_lt_i32 s52, 11
	s_cselect_b64 s[0:1], -1, 0
	s_cmp_gt_i32 s53, 10
	s_cselect_b64 s[2:3], -1, 0
	s_and_b64 s[2:3], s[0:1], s[2:3]
	s_andn2_b64 vcc, exec, s[2:3]
	s_cbranch_vccnz .LBB0_1096
	s_add_u32 s6, s50, 0x9fd0500
	v_lshlrev_b32_e32 v1, 2, v206
	s_addc_u32 s7, s51, 0
	s_ashr_i32 s89, s88, 31
	s_movk_i32 s0, 0x100
	s_waitcnt vmcnt(0)
	v_add_u32_e32 v2, 0, v1
	s_ashr_i32 s24, s54, 31
	s_mov_b32 s25, s54
	v_cmp_gt_u32_e64 s[4:5], s0, v206
	s_mov_b32 s12, 0
	v_add_u32_e32 v6, 0x20000, v2
	s_waitcnt lgkmcnt(0)
	v_mov_b64_e32 v[2:3], 0xaff
	s_movk_i32 s13, 0x161
	v_mov_b32_e32 v5, 0
	v_mov_b32_e32 v7, 0x358637bd
	s_mov_b32 s14, 0xf800000
	v_mov_b32_e32 v8, 0x260
	s_mov_b64 s[8:9], s[88:89]
	s_and_saveexec_b64 s[10:11], s[4:5]
	s_cbranch_execz .Lrs10_skip
.Lrs10_pf:
	v_cmp_gt_i64_e32 vcc, s[8:9], v[2:3]
	s_cbranch_vccnz .Lrs10_done
	s_ashr_i32 s0, s8, 31
	s_lshr_b32 s0, s0, 29
	s_add_i32 s0, s8, s0
	s_ashr_i32 s1, s0, 3
	s_and_b32 s0, s0, -8
	s_sub_i32 s0, s8, s0
	s_cmp_lt_i32 s0, 0
	s_cselect_b32 s15, s13, 0x160
	s_mul_i32 s0, s0, s15
	s_add_i32 s0, s0, s1
	s_mul_hi_i32 s1, s0, 0x2e8ba2e9
	s_lshr_b32 s15, s1, 31
	s_ashr_i32 s1, s1, 6
	s_add_i32 s1, s1, s15
	s_lshl_b32 s15, s1, 3
	s_sub_i32 s16, 64, s15
	s_min_i32 s16, s16, 8
	s_abs_i32 s16, s16
	v_cvt_f32_u32_e32 v4, s16
	s_sub_i32 s17, 0, s16
	s_mulk_i32 s1, 0x160
	s_sub_i32 s0, s0, s1
	v_rcp_iflag_f32_e32 v4, v4
	s_ashr_i32 s1, s0, 31
	s_abs_i32 s0, s0
	v_mul_f32_e32 v4, 0x4f7ffffe, v4
	v_cvt_u32_f32_e32 v4, v4
	s_nop 0
	v_readfirstlane_b32 s18, v4
	s_mul_i32 s17, s17, s18
	s_mul_hi_u32 s17, s18, s17
	s_add_i32 s18, s18, s17
	s_mul_hi_u32 s17, s0, s18
	s_mul_i32 s17, s17, s16
	s_sub_i32 s0, s0, s17
	s_sub_i32 s17, s0, s16
	s_cmp_ge_u32 s0, s16
	s_cselect_b32 s0, s17, s0
	s_sub_i32 s17, s0, s16
	s_cmp_ge_u32 s0, s16
	s_cselect_b32 s0, s17, s0
	s_xor_b32 s0, s0, s1
	s_sub_i32 s0, s0, s1
	s_add_i32 s0, s0, s15
	v_lshl_or_b32 v4, s0, 8, v206
	v_lshl_add_u64 v[10:11], v[4:5], 2, s[6:7]
	global_load_dword v14, v[10:11], off
	s_addk_i32 s12, 0x400
	s_add_u32 s8, s8, s25
	s_addc_u32 s9, s9, s24
	s_cmpk_lg_i32 s12, 0x4000
	s_cbranch_scc1 .Lrs10_pf
.Lrs10_done:
	s_waitcnt vmcnt(0)
	s_mov_b32 s12, 0
	s_mov_b64 s[8:9], s[88:89]
.Lrs10_skip:
	s_or_b64 exec, exec, s[10:11]
	s_branch .LBB0_1081
